# prompt/memory attention: cross-row max via v_permlane16/32_swap instead of two dependent ds_bpermute
# baseline (speedup 1.0000x reference)
.LBB0_1771:
	s_nop 2
	v_max_f32_e32 v64, v57, v57
	v_max_f32_e32 v65, v56, v56
	v_max_f32_e32 v64, v65, v64
	v_max_f32_e32 v65, v59, v59
	v_max_f32_e32 v66, v58, v58
	v_max_f32_e32 v65, v66, v65
	v_max3_f32 v64, v64, v65, s76
	v_max_f32_e32 v65, v53, v53
	v_max_f32_e32 v66, v52, v52
	v_max_f32_e32 v65, v66, v65
	v_max_f32_e32 v66, v55, v55
	v_max_f32_e32 v67, v54, v54
	v_max_f32_e32 v66, v67, v66
	v_max3_f32 v64, v65, v66, v64
	v_max_f32_e32 v65, v49, v49
	v_max_f32_e32 v66, v48, v48
	v_max_f32_e32 v65, v66, v65
	v_max_f32_e32 v66, v51, v51
	v_max_f32_e32 v67, v50, v50
	v_max_f32_e32 v66, v67, v66
	v_max3_f32 v64, v65, v66, v64
	v_max_f32_e32 v65, v45, v45
	v_max_f32_e32 v66, v44, v44
	v_max_f32_e32 v65, v66, v65
	v_max_f32_e32 v66, v47, v47
	v_max_f32_e32 v67, v46, v46
	v_max_f32_e32 v66, v67, v66
	v_max3_f32 v64, v65, v66, v64
	v_mov_b32_e32 v65, v64
	s_nop 1
	v_permlane16_swap_b32_e32 v64, v65
	v_add_u32_e32 v114, 0x3000, v94
	v_add_u32_e32 v115, 0x3000, v95
	v_add_u32_e32 v116, 0x3000, v96
	v_add_u32_e32 v117, 0x3000, v97
	s_waitcnt lgkmcnt(0)
	v_max_f32_e32 v65, v65, v65
	v_max_f32_e32 v64, v64, v65
	v_mov_b32_e32 v65, v64
	s_nop 1
	v_permlane32_swap_b32_e32 v64, v65
	s_waitcnt lgkmcnt(0)
	v_max3_f32 v69, v107, v64, v65
	v_sub_f32_e32 v56, v56, v69
	v_exp_f32_e32 v56, v56
	v_sub_f32_e32 v57, v57, v69
	v_exp_f32_e32 v57, v57
	v_sub_f32_e32 v58, v58, v69
	v_exp_f32_e32 v58, v58
	v_sub_f32_e32 v59, v59, v69
	v_exp_f32_e32 v59, v59
	v_sub_f32_e32 v52, v52, v69
	v_add_f32_e32 v65, 0, v56
	v_exp_f32_e32 v52, v52
	v_sub_f32_e32 v53, v53, v69
	v_add_f32_e32 v65, v57, v65
	v_exp_f32_e32 v53, v53
	v_sub_f32_e32 v54, v54, v69
	v_add_f32_e32 v65, v58, v65
	v_exp_f32_e32 v54, v54
	v_sub_f32_e32 v55, v55, v69
	v_add_f32_e32 v65, v59, v65
	v_exp_f32_e32 v55, v55
	v_sub_f32_e32 v48, v48, v69
	v_add_f32_e32 v65, v52, v65
	v_exp_f32_e32 v70, v48
	v_sub_f32_e32 v49, v49, v69
	v_add_f32_e32 v65, v53, v65
	v_exp_f32_e32 v71, v49
	v_sub_f32_e32 v49, v50, v69
	v_sub_f32_e32 v64, v107, v69
	v_add_f32_e32 v65, v54, v65
	v_exp_f32_e32 v107, v49
	v_sub_f32_e32 v49, v51, v69
	v_add_f32_e32 v65, v55, v65
	v_exp_f32_e32 v108, v49
	v_sub_f32_e32 v44, v44, v69
	v_add_f32_e32 v48, v70, v65
	v_exp_f32_e32 v109, v44
	v_sub_f32_e32 v44, v45, v69
	v_add_f32_e32 v48, v71, v48
	v_exp_f32_e32 v110, v44
	v_sub_f32_e32 v44, v46, v69
	v_add_f32_e32 v48, v107, v48
	v_exp_f32_e32 v111, v44
	v_sub_f32_e32 v44, v47, v69
	v_add_f32_e32 v48, v108, v48
	v_exp_f32_e32 v112, v44
	v_add_f32_e32 v44, v109, v48
	v_add_f32_e32 v44, v110, v44
	v_exp_f32_e32 v68, v64
	v_add_f32_e32 v44, v111, v44
	v_add_f32_e32 v113, v112, v44
	v_cvt_pk_bf16_f32 v44, v56, v57
	v_cvt_pk_bf16_f32 v45, v58, v59
	v_cvt_pk_bf16_f32 v46, v52, v53
	v_cvt_pk_bf16_f32 v47, v54, v55
	ds_read2_b64 v[48:51], v114 offset0:128 offset1:132
	ds_read2_b64 v[52:55], v115 offset0:128 offset1:132
	ds_read2_b64 v[56:59], v116 offset0:128 offset1:132
	ds_read2_b64 v[64:67], v117 offset0:128 offset1:132
	v_pk_mul_f32 v[38:39], v[38:39], v[68:69] op_sel_hi:[1,0]
	v_pk_mul_f32 v[36:37], v[36:37], v[68:69] op_sel_hi:[1,0]
	v_pk_mul_f32 v[34:35], v[34:35], v[68:69] op_sel_hi:[1,0]
	v_pk_mul_f32 v[32:33], v[32:33], v[68:69] op_sel_hi:[1,0]
	v_pk_mul_f32 v[30:31], v[30:31], v[68:69] op_sel_hi:[1,0]
	v_pk_mul_f32 v[28:29], v[28:29], v[68:69] op_sel_hi:[1,0]
	v_pk_mul_f32 v[42:43], v[42:43], v[68:69] op_sel_hi:[1,0]
	v_pk_mul_f32 v[40:41], v[40:41], v[68:69] op_sel_hi:[1,0]
	s_waitcnt lgkmcnt(3)
	v_mfma_f32_16x16x32_bf16 v[36:39], v[48:51], v[44:47], v[36:39]
	s_waitcnt lgkmcnt(2)
	v_mfma_f32_16x16x32_bf16 v[32:35], v[52:55], v[44:47], v[32:35]
	s_waitcnt lgkmcnt(1)
	v_mfma_f32_16x16x32_bf16 v[28:31], v[56:59], v[44:47], v[28:31]
	s_waitcnt lgkmcnt(0)
	v_mfma_f32_16x16x32_bf16 v[40:43], v[64:67], v[44:47], v[40:43]
	ds_read2_b64 v[48:51], v114 offset0:136 offset1:140
	ds_read2_b64 v[52:55], v115 offset0:136 offset1:140
	ds_read2_b64 v[56:59], v116 offset0:136 offset1:140
	ds_read2_b64 v[64:67], v117 offset0:136 offset1:140
	v_cvt_pk_bf16_f32 v44, v70, v71
	v_cvt_pk_bf16_f32 v45, v107, v108
	v_cvt_pk_bf16_f32 v46, v109, v110
	v_cvt_pk_bf16_f32 v47, v111, v112
	s_waitcnt lgkmcnt(3)
	v_mfma_f32_16x16x32_bf16 v[36:39], v[48:51], v[44:47], v[36:39]
	v_fmac_f32_e32 v113, v0, v68
	v_mov_b32_e32 v107, v69
	v_mov_b32_e32 v0, v113
	s_waitcnt lgkmcnt(2)
	v_mfma_f32_16x16x32_bf16 v[32:35], v[52:55], v[44:47], v[32:35]
	s_waitcnt lgkmcnt(1)
	v_mfma_f32_16x16x32_bf16 v[28:31], v[56:59], v[44:47], v[28:31]
	s_waitcnt lgkmcnt(0)
	v_mfma_f32_16x16x32_bf16 v[40:43], v[64:67], v[44:47], v[40:43]

.LBB0_1793:
	s_nop 2
	v_max_f32_e32 v2, v69, v69
	v_max_f32_e32 v3, v68, v68
	v_max_f32_e32 v2, v3, v2
	v_max_f32_e32 v3, v71, v71
	v_max_f32_e32 v106, v70, v70
	v_max_f32_e32 v3, v106, v3
	v_max3_f32 v2, v2, v3, s76
	v_max_f32_e32 v3, v65, v65
	v_max_f32_e32 v106, v64, v64
	v_max_f32_e32 v3, v106, v3
	v_max_f32_e32 v106, v67, v67
	v_max_f32_e32 v108, v66, v66
	v_max_f32_e32 v106, v108, v106
	v_max3_f32 v2, v3, v106, v2
	v_max_f32_e32 v3, v61, v61
	v_max_f32_e32 v106, v60, v60
	v_max_f32_e32 v3, v106, v3
	v_max_f32_e32 v106, v63, v63
	v_max_f32_e32 v108, v62, v62
	v_max_f32_e32 v106, v108, v106
	v_max3_f32 v2, v3, v106, v2
	v_max_f32_e32 v3, v57, v57
	v_max_f32_e32 v106, v56, v56
	v_max_f32_e32 v3, v106, v3
	v_max_f32_e32 v106, v59, v59
	v_max_f32_e32 v108, v58, v58
	v_max_f32_e32 v106, v108, v106
	v_max3_f32 v2, v3, v106, v2
	v_mov_b32_e32 v3, v2
	s_nop 1
	v_permlane16_swap_b32_e32 v2, v3
	v_add_u32_e32 v118, 0x3000, v94
	v_add_u32_e32 v119, 0x3000, v95
	v_add_u32_e32 v120, 0x3000, v96
	v_add_u32_e32 v121, 0x3000, v97
	s_waitcnt lgkmcnt(0)
	v_max_f32_e32 v3, v3, v3
	v_max_f32_e32 v2, v2, v3
	v_mov_b32_e32 v3, v2
	s_nop 1
	v_permlane32_swap_b32_e32 v2, v3
	s_waitcnt lgkmcnt(0)
	v_max3_f32 v2, v107, v2, v3
	v_sub_f32_e32 v68, v68, v2
	v_exp_f32_e32 v68, v68
	v_sub_f32_e32 v69, v69, v2
	v_exp_f32_e32 v69, v69
	v_sub_f32_e32 v70, v70, v2
	v_exp_f32_e32 v70, v70
	v_sub_f32_e32 v71, v71, v2
	v_exp_f32_e32 v71, v71
	v_sub_f32_e32 v64, v64, v2
	v_add_f32_e32 v106, 0, v68
	v_exp_f32_e32 v64, v64
	v_sub_f32_e32 v65, v65, v2
	v_add_f32_e32 v106, v69, v106
	v_exp_f32_e32 v65, v65
	v_sub_f32_e32 v66, v66, v2
	v_add_f32_e32 v106, v70, v106
	v_exp_f32_e32 v66, v66
	v_sub_f32_e32 v67, v67, v2
	v_add_f32_e32 v106, v71, v106
	v_exp_f32_e32 v67, v67
	v_sub_f32_e32 v60, v60, v2
	v_add_f32_e32 v106, v64, v106
	v_exp_f32_e32 v110, v60
	v_sub_f32_e32 v61, v61, v2
	v_add_f32_e32 v106, v65, v106
	v_exp_f32_e32 v111, v61
	v_sub_f32_e32 v61, v62, v2
	v_sub_f32_e32 v56, v56, v2
	v_add_f32_e32 v106, v66, v106
	v_exp_f32_e32 v112, v61
	v_sub_f32_e32 v61, v63, v2
	v_exp_f32_e32 v114, v56
	v_sub_f32_e32 v56, v57, v2
	v_sub_f32_e32 v3, v107, v2
	v_add_f32_e32 v106, v67, v106
	v_exp_f32_e32 v113, v61
	v_exp_f32_e32 v115, v56
	v_sub_f32_e32 v56, v58, v2
	v_sub_f32_e32 v2, v59, v2
	v_add_f32_e32 v60, v110, v106
	v_exp_f32_e32 v117, v2
	v_exp_f32_e32 v2, v3
	v_add_f32_e32 v60, v111, v60
	v_add_f32_e32 v60, v112, v60
	v_add_f32_e32 v60, v113, v60
	v_exp_f32_e32 v116, v56
	v_pk_mul_f32 v[38:39], v[38:39], v[2:3] op_sel_hi:[1,0]
	v_pk_mul_f32 v[36:37], v[36:37], v[2:3] op_sel_hi:[1,0]
	v_pk_mul_f32 v[34:35], v[34:35], v[2:3] op_sel_hi:[1,0]
	v_pk_mul_f32 v[32:33], v[32:33], v[2:3] op_sel_hi:[1,0]
	v_pk_mul_f32 v[30:31], v[30:31], v[2:3] op_sel_hi:[1,0]
	v_pk_mul_f32 v[28:29], v[28:29], v[2:3] op_sel_hi:[1,0]
	v_pk_mul_f32 v[42:43], v[42:43], v[2:3] op_sel_hi:[1,0]
	v_pk_mul_f32 v[40:41], v[40:41], v[2:3] op_sel_hi:[1,0]
	v_add_f32_e32 v3, v114, v60
	v_cvt_pk_bf16_f32 v56, v68, v69
	v_cvt_pk_bf16_f32 v57, v70, v71
	v_cvt_pk_bf16_f32 v58, v64, v65
	v_cvt_pk_bf16_f32 v59, v66, v67
	ds_read2_b64 v[60:63], v118 offset0:128 offset1:132
	ds_read2_b64 v[64:67], v119 offset0:128 offset1:132
	ds_read2_b64 v[68:71], v120 offset0:128 offset1:132
	ds_read2_b64 v[106:109], v121 offset0:128 offset1:132
	v_add_f32_e32 v3, v115, v3
	v_add_f32_e32 v3, v116, v3
	v_add_f32_e32 v3, v117, v3
	s_waitcnt lgkmcnt(3)
	v_mfma_f32_16x16x32_bf16 v[36:39], v[60:63], v[56:59], v[36:39]
	s_waitcnt lgkmcnt(2)
	v_mfma_f32_16x16x32_bf16 v[32:35], v[64:67], v[56:59], v[32:35]
	s_waitcnt lgkmcnt(1)
	v_mfma_f32_16x16x32_bf16 v[28:31], v[68:71], v[56:59], v[28:31]
	s_waitcnt lgkmcnt(0)
	v_mfma_f32_16x16x32_bf16 v[40:43], v[106:109], v[56:59], v[40:43]
	ds_read2_b64 v[60:63], v118 offset0:136 offset1:140
	ds_read2_b64 v[64:67], v119 offset0:136 offset1:140
	ds_read2_b64 v[68:71], v120 offset0:136 offset1:140
	ds_read2_b64 v[106:109], v121 offset0:136 offset1:140
	v_cvt_pk_bf16_f32 v56, v110, v111
	v_cvt_pk_bf16_f32 v57, v112, v113
	v_cvt_pk_bf16_f32 v58, v114, v115
	v_cvt_pk_bf16_f32 v59, v116, v117
	s_waitcnt lgkmcnt(3)
	v_mfma_f32_16x16x32_bf16 v[36:39], v[60:63], v[56:59], v[36:39]
	v_fmac_f32_e32 v3, v0, v2
	v_mov_b32_e32 v0, v3
	s_waitcnt lgkmcnt(2)
	v_mfma_f32_16x16x32_bf16 v[32:35], v[64:67], v[56:59], v[32:35]
	s_waitcnt lgkmcnt(1)
	v_mfma_f32_16x16x32_bf16 v[28:31], v[68:71], v[56:59], v[28:31]
	s_waitcnt lgkmcnt(0)
	v_mfma_f32_16x16x32_bf16 v[40:43], v[106:109], v[56:59], v[40:43]

.LBB0_1833:
	s_or_b64 exec, exec, s[16:17]
	v_lshl_add_u64 v[10:11], s[4:5], 0, v[66:67]
	v_lshl_add_u64 v[14:15], s[4:5], 0, v[68:69]
	global_load_dwordx4 v[10:13], v[10:11], off
	s_nop 0
	global_load_dwordx4 v[14:17], v[14:15], off
	ds_read_b128 v[76:79], v83
	ds_read_b128 v[124:127], v83 offset:64
	ds_read_b128 v[134:137], v83 offset:128
	ds_read_b128 v[138:141], v83 offset:192
	ds_read_b128 v[142:145], v83 offset:4352
	ds_read_b128 v[146:149], v83 offset:4416
	ds_read_b128 v[150:153], v83 offset:4480
	ds_read_b128 v[154:157], v83 offset:4544
	ds_read_b128 v[158:161], v83 offset:8704
	ds_read_b128 v[162:165], v83 offset:8768
	ds_read_b128 v[166:169], v83 offset:8832
	ds_read_b128 v[170:173], v83 offset:8896
	ds_read_b128 v[174:177], v83 offset:13056
	ds_read_b128 v[178:181], v83 offset:13120
	ds_read_b128 v[182:185], v83 offset:13184
	ds_read_b128 v[186:189], v83 offset:13248
	s_waitcnt lgkmcnt(14)
	v_mfma_f32_16x16x32_bf16 v[76:79], v[76:79], v[18:21], 0
	v_add_u32_e32 v128, 0x4000, v116
	v_add_u32_e32 v133, 0x4000, v117
	v_add_u32_e32 v129, 0x8000, v114
	s_waitcnt lgkmcnt(11)
	v_mfma_f32_16x16x32_bf16 v[142:145], v[142:145], v[18:21], 0
	v_mfma_f32_16x16x32_bf16 v[76:79], v[124:127], v[22:25], v[76:79]
	s_waitcnt lgkmcnt(7)
	v_mfma_f32_16x16x32_bf16 v[158:161], v[158:161], v[18:21], 0
	v_mfma_f32_16x16x32_bf16 v[124:127], v[146:149], v[22:25], v[142:145]
	v_mfma_f32_16x16x32_bf16 v[76:79], v[134:137], v[26:29], v[76:79]
	s_waitcnt lgkmcnt(3)
	v_mfma_f32_16x16x32_bf16 v[174:177], v[174:177], v[18:21], 0
	v_mfma_f32_16x16x32_bf16 v[142:145], v[162:165], v[22:25], v[158:161]
	v_mfma_f32_16x16x32_bf16 v[124:127], v[150:153], v[26:29], v[124:127]
	s_nop 1
	ds_read2_b64 v[160:163], v129 offset0:96 offset1:100
	v_mfma_f32_16x16x32_bf16 v[76:79], v[138:141], v[30:33], v[76:79]
	v_mfma_f32_16x16x32_bf16 v[134:137], v[166:169], v[26:29], v[142:145]
	s_waitcnt lgkmcnt(3)
	v_mfma_f32_16x16x32_bf16 v[140:143], v[178:181], v[22:25], v[174:177]
	s_nop 4
	v_max_f32_e32 v75, v77, v77
	v_max_f32_e32 v80, v76, v76
	v_max_f32_e32 v75, v80, v75
	v_mfma_f32_16x16x32_bf16 v[124:127], v[154:157], v[30:33], v[124:127]
	v_max_f32_e32 v80, v79, v79
	v_max_f32_e32 v81, v78, v78
	v_max_f32_e32 v80, v81, v80
	s_waitcnt lgkmcnt(2)
	v_mfma_f32_16x16x32_bf16 v[140:143], v[182:185], v[26:29], v[140:143]
	v_max3_f32 v75, v75, v80, s76
	s_nop 1
	v_max_f32_e32 v80, v125, v125
	v_max_f32_e32 v81, v124, v124
	v_mfma_f32_16x16x32_bf16 v[136:139], v[170:173], v[30:33], v[134:137]
	v_max_f32_e32 v80, v81, v80
	v_max_f32_e32 v81, v127, v127
	v_max_f32_e32 v111, v126, v126
	v_max_f32_e32 v81, v111, v81
	s_waitcnt lgkmcnt(1)
	v_mfma_f32_16x16x32_bf16 v[140:143], v[186:189], v[30:33], v[140:143]
	v_max3_f32 v75, v80, v81, v75
	s_nop 0
	v_max_f32_e32 v80, v137, v137
	v_max_f32_e32 v81, v136, v136
	v_max_f32_e32 v80, v81, v80
	v_max_f32_e32 v81, v139, v139
	v_max_f32_e32 v111, v138, v138
	v_max_f32_e32 v81, v111, v81
	v_max3_f32 v75, v80, v81, v75
	v_max_f32_e32 v80, v141, v141
	v_max_f32_e32 v81, v140, v140
	v_max_f32_e32 v80, v81, v80
	v_max_f32_e32 v81, v143, v143
	v_max_f32_e32 v111, v142, v142
	v_max_f32_e32 v81, v111, v81
	v_max3_f32 v75, v80, v81, v75
	v_mov_b32_e32 v80, v75
	s_nop 1
	v_permlane16_swap_b32_e32 v75, v80
	v_add_u32_e32 v134, 0x4000, v114
	ds_read2_b64 v[144:147], v133 offset0:128 offset1:132
	s_waitcnt lgkmcnt(1)
	v_max_f32_e32 v80, v80, v80
	v_max_f32_e32 v75, v75, v80
	v_mov_b32_e32 v80, v75
	s_nop 1
	v_permlane32_swap_b32_e32 v75, v80
	s_waitcnt lgkmcnt(0)
	v_max3_f32 v135, v0, v75, v80
	v_sub_f32_e32 v75, v76, v135
	v_exp_f32_e32 v75, v75
	v_sub_f32_e32 v76, v77, v135
	v_exp_f32_e32 v80, v76
	v_sub_f32_e32 v76, v78, v135
	v_exp_f32_e32 v81, v76
	v_sub_f32_e32 v76, v79, v135
	v_exp_f32_e32 v112, v76
	v_sub_f32_e32 v77, v124, v135
	v_add_f32_e32 v76, 0, v75
	v_exp_f32_e32 v113, v77
	v_sub_f32_e32 v77, v125, v135
	v_add_f32_e32 v76, v80, v76
	v_exp_f32_e32 v166, v77
	v_sub_f32_e32 v77, v126, v135
	v_add_f32_e32 v76, v81, v76
	v_exp_f32_e32 v167, v77
	v_sub_f32_e32 v77, v127, v135
	v_add_f32_e32 v76, v112, v76
	v_exp_f32_e32 v168, v77
	v_sub_f32_e32 v77, v136, v135
	v_add_f32_e32 v76, v113, v76
	v_exp_f32_e32 v169, v77
	v_sub_f32_e32 v77, v137, v135
	v_add_f32_e32 v76, v166, v76
	v_exp_f32_e32 v170, v77
	v_sub_f32_e32 v77, v138, v135
	v_add_f32_e32 v76, v167, v76
	v_exp_f32_e32 v171, v77
	v_sub_f32_e32 v77, v139, v135
	v_add_f32_e32 v76, v168, v76
	v_exp_f32_e32 v172, v77
	v_sub_f32_e32 v77, v140, v135
	v_add_f32_e32 v76, v169, v76
	v_exp_f32_e32 v173, v77
	v_sub_f32_e32 v77, v141, v135
	v_add_f32_e32 v76, v170, v76
	v_exp_f32_e32 v174, v77
	v_sub_f32_e32 v77, v142, v135
	v_add_f32_e32 v76, v171, v76
	v_exp_f32_e32 v175, v77
	v_sub_f32_e32 v77, v143, v135
	v_add_f32_e32 v76, v172, v76
	v_exp_f32_e32 v176, v77
	v_add_f32_e32 v76, v173, v76
	v_sub_f32_e32 v0, v0, v135
	v_add_f32_e32 v76, v174, v76
	v_exp_f32_e32 v0, v0
	v_add_f32_e32 v76, v175, v76
	v_add_u32_e32 v126, 0x4000, v115
	v_add_u32_e32 v124, 0x6800, v114
	v_add_u32_e32 v125, 0x7000, v114
	v_add_u32_e32 v127, 0x7800, v114
	v_add_f32_e32 v111, v176, v76
	ds_read2_b64 v[76:79], v134 offset0:128 offset1:132
	ds_read2_b64 v[136:139], v126 offset0:128 offset1:132
	ds_read2_b64 v[140:143], v128 offset0:128 offset1:132
	ds_read2_b64 v[148:151], v124 offset1:4
	ds_read2_b64 v[152:155], v125 offset0:32 offset1:36
	ds_read2_b64 v[156:159], v127 offset0:64 offset1:68
	v_pk_mul_f32 v[72:73], v[72:73], v[0:1] op_sel_hi:[1,0]
	v_pk_mul_f32 v[70:71], v[70:71], v[0:1] op_sel_hi:[1,0]
	v_pk_mul_f32 v[64:65], v[64:65], v[0:1] op_sel_hi:[1,0]
	v_pk_mul_f32 v[62:63], v[62:63], v[0:1] op_sel_hi:[1,0]
	v_pk_mul_f32 v[56:57], v[56:57], v[0:1] op_sel_hi:[1,0]
	v_pk_mul_f32 v[54:55], v[54:55], v[0:1] op_sel_hi:[1,0]
	v_pk_mul_f32 v[52:53], v[52:53], v[0:1] op_sel_hi:[1,0]
	v_pk_mul_f32 v[50:51], v[50:51], v[0:1] op_sel_hi:[1,0]
	v_pk_mul_f32 v[44:45], v[44:45], v[0:1] op_sel_hi:[1,0]
	v_pk_mul_f32 v[42:43], v[42:43], v[0:1] op_sel_hi:[1,0]
	v_pk_mul_f32 v[36:37], v[36:37], v[0:1] op_sel_hi:[1,0]
	v_pk_mul_f32 v[34:35], v[34:35], v[0:1] op_sel_hi:[1,0]
	v_pk_mul_f32 v[48:49], v[48:49], v[0:1] op_sel_hi:[1,0]
	v_pk_mul_f32 v[46:47], v[46:47], v[0:1] op_sel_hi:[1,0]
	v_pk_mul_f32 v[40:41], v[40:41], v[0:1] op_sel_hi:[1,0]
	v_pk_mul_f32 v[38:39], v[38:39], v[0:1] op_sel_hi:[1,0]
	v_cvt_pk_bf16_f32 v164, v75, v80
	v_cvt_pk_bf16_f32 v165, v81, v112
	v_cvt_pk_bf16_f32 v166, v113, v166
	v_cvt_pk_bf16_f32 v167, v167, v168
	s_waitcnt lgkmcnt(5)
	v_mfma_f32_16x16x32_bf16 v[70:73], v[76:79], v[164:167], v[70:73]
	v_cvt_pk_bf16_f32 v76, v169, v170
	v_cvt_pk_bf16_f32 v77, v171, v172
	v_cvt_pk_bf16_f32 v78, v173, v174
	s_waitcnt lgkmcnt(4)
	v_mfma_f32_16x16x32_bf16 v[62:65], v[136:139], v[164:167], v[62:65]
	v_cvt_pk_bf16_f32 v79, v175, v176
	s_waitcnt lgkmcnt(3)
	v_mfma_f32_16x16x32_bf16 v[54:57], v[140:143], v[164:167], v[54:57]
	v_mfma_f32_16x16x32_bf16 v[50:53], v[144:147], v[164:167], v[50:53]
	s_waitcnt lgkmcnt(2)
	v_mfma_f32_16x16x32_bf16 v[42:45], v[148:151], v[164:167], v[42:45]
	s_waitcnt lgkmcnt(1)
	v_mfma_f32_16x16x32_bf16 v[34:37], v[152:155], v[164:167], v[34:37]
	s_waitcnt lgkmcnt(0)
	v_mfma_f32_16x16x32_bf16 v[46:49], v[156:159], v[164:167], v[46:49]
	v_mfma_f32_16x16x32_bf16 v[38:41], v[160:163], v[164:167], v[38:41]
	ds_read2_b64 v[136:139], v134 offset0:136 offset1:140
	ds_read2_b64 v[140:143], v126 offset0:136 offset1:140
	ds_read2_b64 v[144:147], v128 offset0:136 offset1:140
	ds_read2_b64 v[148:151], v133 offset0:136 offset1:140
	ds_read2_b64 v[152:155], v124 offset0:8 offset1:12
	ds_read2_b64 v[156:159], v125 offset0:40 offset1:44
	ds_read2_b64 v[160:163], v127 offset0:72 offset1:76
	ds_read2_b64 v[164:167], v129 offset0:104 offset1:108
	s_waitcnt lgkmcnt(7)
	v_mfma_f32_16x16x32_bf16 v[70:73], v[136:139], v[76:79], v[70:73]
	s_add_i32 s18, s18, -1
	v_fmac_f32_e32 v111, v74, v0
	v_lshl_add_u64 v[58:59], v[58:59], 0, s[26:27]
	s_waitcnt lgkmcnt(6)
	v_mfma_f32_16x16x32_bf16 v[62:65], v[140:143], v[76:79], v[62:65]
	v_lshl_add_u64 v[60:61], v[60:61], 0, s[26:27]
	v_lshl_add_u64 v[66:67], v[66:67], 0, s[22:23]
	v_lshl_add_u64 v[68:69], v[68:69], 0, s[22:23]
	s_waitcnt lgkmcnt(5)
	v_mfma_f32_16x16x32_bf16 v[54:57], v[144:147], v[76:79], v[54:57]
	s_cmp_eq_u32 s18, 0
	s_waitcnt lgkmcnt(4)
	v_mfma_f32_16x16x32_bf16 v[50:53], v[148:151], v[76:79], v[50:53]
	s_waitcnt lgkmcnt(3)
	v_mfma_f32_16x16x32_bf16 v[42:45], v[152:155], v[76:79], v[42:45]
	s_waitcnt lgkmcnt(2)
	v_mfma_f32_16x16x32_bf16 v[34:37], v[156:159], v[76:79], v[34:37]
	s_waitcnt lgkmcnt(1)
	v_mfma_f32_16x16x32_bf16 v[46:49], v[160:163], v[76:79], v[46:49]
	s_waitcnt lgkmcnt(0)
	v_mfma_f32_16x16x32_bf16 v[38:41], v[164:167], v[76:79], v[38:41]
	s_cbranch_scc1 .LBB0_1835
	v_mov_b32_e32 v0, v135
	v_mov_b32_e32 v74, v111
	s_branch .LBB0_1825

.LBB0_1853:
.LBB0_1854:
	ds_read_b128 v[136:139], v83
	ds_read_b128 v[140:143], v83 offset:64
	ds_read_b128 v[144:147], v83 offset:128
	ds_read_b128 v[148:151], v83 offset:192
	ds_read_b128 v[152:155], v83 offset:4352
	ds_read_b128 v[156:159], v83 offset:4416
	ds_read_b128 v[160:163], v83 offset:4480
	ds_read_b128 v[164:167], v83 offset:4544
	ds_read_b128 v[168:171], v83 offset:8704
	ds_read_b128 v[172:175], v83 offset:8768
	ds_read_b128 v[176:179], v83 offset:8832
	ds_read_b128 v[180:183], v83 offset:8896
	ds_read_b128 v[184:187], v83 offset:13056
	ds_read_b128 v[188:191], v83 offset:13120
	ds_read_b128 v[192:195], v83 offset:13184
	ds_read_b128 v[196:199], v83 offset:13248
	s_waitcnt lgkmcnt(14)
	v_mfma_f32_16x16x32_bf16 v[136:139], v[136:139], v[18:21], 0
	s_waitcnt lgkmcnt(11)
	v_mfma_f32_16x16x32_bf16 v[152:155], v[152:155], v[18:21], 0
	v_mfma_f32_16x16x32_bf16 v[136:139], v[140:143], v[22:25], v[136:139]
	s_waitcnt lgkmcnt(7)
	v_mfma_f32_16x16x32_bf16 v[168:171], v[168:171], v[18:21], 0
	v_mfma_f32_16x16x32_bf16 v[140:143], v[156:159], v[22:25], v[152:155]
	s_waitcnt lgkmcnt(3)
	v_mfma_f32_16x16x32_bf16 v[18:21], v[184:187], v[18:21], 0
	v_mfma_f32_16x16x32_bf16 v[136:139], v[144:147], v[26:29], v[136:139]
	v_mfma_f32_16x16x32_bf16 v[152:155], v[172:175], v[22:25], v[168:171]
	v_mfma_f32_16x16x32_bf16 v[140:143], v[160:163], v[26:29], v[140:143]
	v_mfma_f32_16x16x32_bf16 v[136:139], v[148:151], v[30:33], v[136:139]
	s_waitcnt lgkmcnt(2)
	v_mfma_f32_16x16x32_bf16 v[18:21], v[188:191], v[22:25], v[18:21]
	v_mfma_f32_16x16x32_bf16 v[144:147], v[176:179], v[26:29], v[152:155]
	s_nop 4
	v_max_f32_e32 v0, v137, v137
	v_max_f32_e32 v112, v136, v136
	v_max_f32_e32 v0, v112, v0
	v_mfma_f32_16x16x32_bf16 v[140:143], v[164:167], v[30:33], v[140:143]
	v_max_f32_e32 v112, v139, v139
	v_max_f32_e32 v113, v138, v138
	v_max_f32_e32 v112, v113, v112
	s_waitcnt lgkmcnt(1)
	v_mfma_f32_16x16x32_bf16 v[18:21], v[192:195], v[26:29], v[18:21]
	v_max3_f32 v0, v0, v112, s76
	s_nop 1
	v_max_f32_e32 v112, v141, v141
	v_max_f32_e32 v113, v140, v140
	v_mfma_f32_16x16x32_bf16 v[144:147], v[180:183], v[30:33], v[144:147]
	v_max_f32_e32 v112, v113, v112
	v_max_f32_e32 v113, v143, v143
	v_max_f32_e32 v148, v142, v142
	s_waitcnt lgkmcnt(0)
	v_mfma_f32_16x16x32_bf16 v[18:21], v[196:199], v[30:33], v[18:21]
	v_max_f32_e32 v113, v148, v113
	v_max3_f32 v0, v112, v113, v0
	s_nop 0
	v_max_f32_e32 v112, v145, v145
	v_max_f32_e32 v22, v144, v144
	v_max_f32_e32 v23, v147, v147
	v_max_f32_e32 v24, v146, v146
	v_max_f32_e32 v22, v22, v112
	v_max_f32_e32 v23, v24, v23
	v_max3_f32 v0, v22, v23, v0
	v_max_f32_e32 v22, v19, v19
	v_max_f32_e32 v23, v18, v18
	v_max_f32_e32 v22, v23, v22
	v_max_f32_e32 v23, v21, v21
	v_max_f32_e32 v24, v20, v20
	v_max_f32_e32 v23, v24, v23
	v_max3_f32 v0, v22, v23, v0
	v_mov_b32_e32 v22, v0
	s_nop 1
	v_permlane16_swap_b32_e32 v0, v22
	s_waitcnt lgkmcnt(0)
	v_max_f32_e32 v22, v22, v22
	v_max_f32_e32 v0, v0, v22
	v_mov_b32_e32 v22, v0
	s_nop 1
	v_permlane32_swap_b32_e32 v0, v22
	s_waitcnt lgkmcnt(0)
	v_max3_f32 v22, v135, v0, v22
	v_sub_f32_e32 v23, v136, v22
	v_exp_f32_e32 v112, v23
	v_sub_f32_e32 v23, v137, v22
	v_exp_f32_e32 v113, v23
	v_sub_f32_e32 v23, v138, v22
	v_sub_f32_e32 v0, v135, v22
	v_exp_f32_e32 v135, v23
	v_sub_f32_e32 v23, v139, v22
	v_exp_f32_e32 v153, v23
	v_sub_f32_e32 v24, v140, v22
	v_add_f32_e32 v23, 0, v112
	v_exp_f32_e32 v154, v24
	v_sub_f32_e32 v24, v141, v22
	v_add_f32_e32 v23, v113, v23
	v_exp_f32_e32 v155, v24
	v_sub_f32_e32 v24, v142, v22
	v_add_f32_e32 v23, v135, v23
	v_exp_f32_e32 v156, v24
	v_sub_f32_e32 v24, v143, v22
	v_add_f32_e32 v23, v153, v23
	v_exp_f32_e32 v157, v24
	v_sub_f32_e32 v24, v144, v22
	v_add_f32_e32 v23, v154, v23
	v_exp_f32_e32 v158, v24
	v_sub_f32_e32 v24, v145, v22
	v_add_f32_e32 v23, v155, v23
	v_exp_f32_e32 v159, v24
	v_sub_f32_e32 v24, v146, v22
	v_add_f32_e32 v23, v156, v23
	v_exp_f32_e32 v160, v24
	v_sub_f32_e32 v24, v147, v22
	v_add_f32_e32 v23, v157, v23
	v_exp_f32_e32 v161, v24
	v_sub_f32_e32 v18, v18, v22
	v_add_f32_e32 v23, v158, v23
	v_exp_f32_e32 v162, v18
	v_sub_f32_e32 v18, v19, v22
	v_exp_f32_e32 v0, v0
	v_add_f32_e32 v23, v159, v23
	v_exp_f32_e32 v163, v18
	v_sub_f32_e32 v18, v20, v22
	v_add_f32_e32 v23, v160, v23
	v_exp_f32_e32 v164, v18
	v_sub_f32_e32 v18, v21, v22
	v_add_f32_e32 v136, v161, v23
	v_exp_f32_e32 v165, v18
	v_pk_mul_f32 v[30:31], v[50:51], v[0:1] op_sel_hi:[1,0]
	v_add_f32_e32 v50, v162, v136
	v_add_f32_e32 v50, v163, v50
	v_add_f32_e32 v50, v164, v50
	v_pk_mul_f32 v[20:21], v[72:73], v[0:1] op_sel_hi:[1,0]
	v_pk_mul_f32 v[18:19], v[70:71], v[0:1] op_sel_hi:[1,0]
	v_pk_mul_f32 v[24:25], v[64:65], v[0:1] op_sel_hi:[1,0]
	v_pk_mul_f32 v[22:23], v[62:63], v[0:1] op_sel_hi:[1,0]
	v_pk_mul_f32 v[28:29], v[56:57], v[0:1] op_sel_hi:[1,0]
	v_pk_mul_f32 v[26:27], v[54:55], v[0:1] op_sel_hi:[1,0]
	v_pk_mul_f32 v[32:33], v[52:53], v[0:1] op_sel_hi:[1,0]
	v_add_f32_e32 v166, v165, v50
	ds_read2_b64 v[50:53], v134 offset0:128 offset1:132
	ds_read2_b64 v[54:57], v126 offset0:128 offset1:132
	ds_read2_b64 v[62:65], v128 offset0:128 offset1:132
	ds_read2_b64 v[70:73], v133 offset0:128 offset1:132
	ds_read2_b64 v[136:139], v124 offset1:4
	ds_read2_b64 v[140:143], v125 offset0:32 offset1:36
	ds_read2_b64 v[144:147], v127 offset0:64 offset1:68
	ds_read2_b64 v[148:151], v129 offset0:96 offset1:100
	v_pk_mul_f32 v[44:45], v[44:45], v[0:1] op_sel_hi:[1,0]
	v_pk_mul_f32 v[42:43], v[42:43], v[0:1] op_sel_hi:[1,0]
	v_pk_mul_f32 v[36:37], v[36:37], v[0:1] op_sel_hi:[1,0]
	v_pk_mul_f32 v[34:35], v[34:35], v[0:1] op_sel_hi:[1,0]
	v_pk_mul_f32 v[48:49], v[48:49], v[0:1] op_sel_hi:[1,0]
	v_pk_mul_f32 v[46:47], v[46:47], v[0:1] op_sel_hi:[1,0]
	v_pk_mul_f32 v[40:41], v[40:41], v[0:1] op_sel_hi:[1,0]
	v_pk_mul_f32 v[38:39], v[38:39], v[0:1] op_sel_hi:[1,0]
	v_cvt_pk_bf16_f32 v152, v112, v113
	v_cvt_pk_bf16_f32 v153, v135, v153
	v_cvt_pk_bf16_f32 v154, v154, v155
	v_cvt_pk_bf16_f32 v155, v156, v157
	s_waitcnt lgkmcnt(7)
	v_mfma_f32_16x16x32_bf16 v[18:21], v[50:53], v[152:155], v[18:21]
	s_waitcnt lgkmcnt(6)
	v_mfma_f32_16x16x32_bf16 v[22:25], v[54:57], v[152:155], v[22:25]
	s_waitcnt lgkmcnt(5)
	v_mfma_f32_16x16x32_bf16 v[26:29], v[62:65], v[152:155], v[26:29]
	s_waitcnt lgkmcnt(4)
	v_mfma_f32_16x16x32_bf16 v[30:33], v[70:73], v[152:155], v[30:33]
	s_waitcnt lgkmcnt(3)
	v_mfma_f32_16x16x32_bf16 v[50:53], v[136:139], v[152:155], v[42:45]
	v_cvt_pk_bf16_f32 v136, v158, v159
	v_cvt_pk_bf16_f32 v137, v160, v161
	v_cvt_pk_bf16_f32 v138, v162, v163
	s_waitcnt lgkmcnt(2)
	v_mfma_f32_16x16x32_bf16 v[54:57], v[140:143], v[152:155], v[34:37]
	v_cvt_pk_bf16_f32 v139, v164, v165
	s_waitcnt lgkmcnt(1)
	v_mfma_f32_16x16x32_bf16 v[62:65], v[144:147], v[152:155], v[46:49]
	s_waitcnt lgkmcnt(0)
	v_mfma_f32_16x16x32_bf16 v[70:73], v[148:151], v[152:155], v[38:41]
	ds_read2_b64 v[34:37], v134 offset0:136 offset1:140
	s_nop 1
	ds_read2_b64 v[38:41], v126 offset0:136 offset1:140
	ds_read2_b64 v[140:143], v128 offset0:136 offset1:140
	ds_read2_b64 v[144:147], v133 offset0:136 offset1:140
	ds_read2_b64 v[148:151], v124 offset0:8 offset1:12
	ds_read2_b64 v[152:155], v125 offset0:40 offset1:44
	ds_read2_b64 v[124:127], v127 offset0:72 offset1:76
	ds_read2_b64 v[156:159], v129 offset0:104 offset1:108
	v_fmac_f32_e32 v166, v111, v0
	ds_bpermute_b32 v0, v85, v166
	s_waitcnt lgkmcnt(8)
	v_mfma_f32_16x16x32_bf16 v[46:49], v[34:37], v[136:139], v[18:21]
	v_cmp_gt_i32_e32 vcc, s49, v82
	s_waitcnt lgkmcnt(0)
	v_add_f32_e32 v0, v166, v0
	v_mfma_f32_16x16x32_bf16 v[34:37], v[144:147], v[136:139], v[30:33]
	v_mfma_f32_16x16x32_bf16 v[30:33], v[148:151], v[136:139], v[50:53]
	s_nop 2
	ds_bpermute_b32 v50, v87, v0
	v_mfma_f32_16x16x32_bf16 v[42:45], v[38:41], v[136:139], v[22:25]
	v_mfma_f32_16x16x32_bf16 v[38:41], v[140:143], v[136:139], v[26:29]
	v_mfma_f32_16x16x32_bf16 v[26:29], v[152:155], v[136:139], v[54:57]
	v_mfma_f32_16x16x32_bf16 v[22:25], v[124:127], v[136:139], v[62:65]
	v_mfma_f32_16x16x32_bf16 v[18:21], v[156:159], v[136:139], v[70:73]
	s_and_saveexec_b64 s[12:13], vcc
	s_cbranch_execz .LBB0_1800
	s_lshl_b64 s[8:9], s[8:9], 1
	s_add_u32 s14, s44, s8
	s_waitcnt lgkmcnt(0)
	v_add_f32_e32 v0, v0, v50
	s_addc_u32 s15, s45, s9
	v_div_scale_f32 v50, s[8:9], v0, v0, 1.0
	v_rcp_f32_e32 v51, v50
	s_lshl_b32 s8, s50, 1
	s_add_u32 s8, s14, s8
	s_addc_u32 s9, s15, 0
	v_fma_f32 v52, -v50, v51, 1.0
	v_fmac_f32_e32 v51, v52, v51
	v_div_scale_f32 v52, vcc, 1.0, v0, 1.0
	v_mul_f32_e32 v53, v52, v51
	v_fma_f32 v54, -v50, v53, v52
	v_fmac_f32_e32 v53, v54, v51
	v_fma_f32 v50, -v50, v53, v52
	v_div_fmas_f32 v50, v50, v51, v53
	v_div_fixup_f32 v0, v50, v0, 1.0
	v_lshl_add_u64 v[50:51], s[8:9], 0, v[96:97]
	v_mov_b32_e32 v111, v1
	v_mul_f32_e32 v46, v46, v0
	v_mul_f32_e32 v47, v47, v0
	v_mul_f32_e32 v42, v42, v0
	v_mul_f32_e32 v43, v43, v0
	v_mul_f32_e32 v38, v38, v0
	v_mul_f32_e32 v39, v39, v0
	v_mul_f32_e32 v34, v34, v0
	v_mul_f32_e32 v35, v35, v0
	v_mul_f32_e32 v30, v30, v0
	v_mul_f32_e32 v31, v31, v0
	v_mul_f32_e32 v26, v26, v0
	v_mul_f32_e32 v27, v27, v0
	v_mul_f32_e32 v22, v22, v0
	v_mul_f32_e32 v23, v23, v0
	v_mul_f32_e32 v18, v18, v0
	v_mul_f32_e32 v19, v19, v0
	v_lshl_add_u64 v[50:51], v[50:51], 0, v[110:111]
	v_cvt_pk_bf16_f32 v46, v46, v47
	v_mul_f32_e32 v47, v48, v0
	v_cvt_pk_bf16_f32 v42, v42, v43
	v_mul_f32_e32 v43, v44, v0
	v_cvt_pk_bf16_f32 v38, v38, v39
	v_mul_f32_e32 v39, v40, v0
	v_cvt_pk_bf16_f32 v34, v34, v35
	v_mul_f32_e32 v35, v36, v0
	v_cvt_pk_bf16_f32 v30, v30, v31
	v_mul_f32_e32 v31, v32, v0
	v_cvt_pk_bf16_f32 v26, v26, v27
	v_mul_f32_e32 v27, v28, v0
	v_cvt_pk_bf16_f32 v22, v22, v23
	v_mul_f32_e32 v23, v24, v0
	v_cvt_pk_bf16_f32 v18, v18, v19
	v_mul_f32_e32 v19, v20, v0
	v_mul_f32_e32 v48, v49, v0
	v_cvt_pk_bf16_f32 v47, v47, v48
	global_store_dwordx2 v[50:51], v[46:47], off
	v_mul_f32_e32 v44, v45, v0
	v_cvt_pk_bf16_f32 v43, v43, v44
	global_store_dwordx2 v[50:51], v[42:43], off offset:32
	v_mul_f32_e32 v40, v41, v0
	v_cvt_pk_bf16_f32 v39, v39, v40
	global_store_dwordx2 v[50:51], v[38:39], off offset:64
	v_mul_f32_e32 v36, v37, v0
	v_cvt_pk_bf16_f32 v35, v35, v36
	global_store_dwordx2 v[50:51], v[34:35], off offset:96
	v_mul_f32_e32 v32, v33, v0
	v_cvt_pk_bf16_f32 v31, v31, v32
	global_store_dwordx2 v[50:51], v[30:31], off offset:128
	v_mul_f32_e32 v28, v29, v0
	v_cvt_pk_bf16_f32 v27, v27, v28
	global_store_dwordx2 v[50:51], v[26:27], off offset:160
	v_mul_f32_e32 v24, v25, v0
	v_cvt_pk_bf16_f32 v23, v23, v24
	global_store_dwordx2 v[50:51], v[22:23], off offset:192
	v_mul_f32_e32 v0, v21, v0
	v_cvt_pk_bf16_f32 v19, v19, v0
	global_store_dwordx2 v[50:51], v[18:19], off offset:224
	s_branch .LBB0_1800
